# P8 prompt row pass hand-written with 16-byte accesses only (y loads / a2 stores dwordx4, DPP+permlane wave sum) + wide P12 row pass
# baseline (speedup 1.0000x reference)
; __device__ __forceinline__ float wave_sum(float v) { for (int o = 32; o >= 1; o >>= 1) v += __shfl_xor(v, o); return v; }
; __device__ __forceinline__ u32x2 pk4(f32x4 v) { u32x2 w; w.x = cvt_pk_bf16(v[0], v[1]); w.y = cvt_pk_bf16(v[2], v[3]); return w; }
; __device__ __forceinline__ f32x4 up4(u32x2 w) { return (f32x4){bf_lo(w.x), bf_hi(w.x), bf_lo(w.y), bf_hi(w.y)}; }
; __device__ __forceinline__ void row_pass1(const Args& a, int row_lo, int row_hi, int gw, int NGW, int lane) {
;     ...
;     for (int r0 = row_lo + 2 * gw; r0 < row_hi; r0 += 2 * NGW) {
;         f32x4 xv[2][4]; u32x2 yv[2][4]; float rs[2];
; #pragma unroll
;         for (int r = 0; r < 2; ++r) { const int row = (r0 + r < row_hi) ? r0 + r : r0; rs[r] = rss[row];
;             const f32x4* xr = (const f32x4*)xrow_ptr(a, row) + lane; const u32x2* yr = (const u32x2*)(Y + (size_t)row * DM) + lane;
; #pragma unroll
;             for (int j = 0; j < 4; ++j) { xv[r][j] = xr[64 * j]; yv[r][j] = yr[64 * j]; } }
; #pragma unroll
;         for (int r = 0; r < 2; ++r) { const int row = r0 + r; if (row >= row_hi) break;
;             const float rstd = rsqrtf(rs[r] * (1.f / DM) + EPS); f32x4 v[4]; float s = 0.f;
; #pragma unroll
;             for (int j = 0; j < 4; ++j) { v[j] = xv[r][j] + up4(yv[r][j]) * rstd * gp[j]; s += (v[j][0] * v[j][0] + v[j][1] * v[j][1]) + (v[j][2] * v[j][2] + v[j][3] * v[j][3]); }
;             const float rstd2 = rsqrtf(wave_sum(s) * (1.f / DM) + EPS);
;             f32x4* xo = (f32x4*)(XO + (size_t)row * DM) + lane; u32x2* ao = (u32x2*)(A2 + (size_t)row * DM) + lane;
; #pragma unroll
;             for (int j = 0; j < 4; ++j) { xo[64 * j] = v[j]; ao[64 * j] = pk4(v[j] * rstd2 * gq[j]); } }
.LBB0_1036:
	s_and_b64 vcc, exec, s[10:11]
	s_cbranch_vccz .LBB0_1042
	s_lshl_b32 s0, s81, 1
	s_add_i32 s8, s0, 0xffffff00
	s_cmpk_gt_i32 s8, 0x3fff
	s_cbranch_scc1 .LBB0_1042
	s_waitcnt vmcnt(0)
	v_readlane_b32 s20, v252, 1
	v_readlane_b32 s21, v252, 2
	v_readlane_b32 s14, v252, 13
	v_readlane_b32 s15, v252, 14
	v_readlane_b32 s18, v252, 15
	v_readlane_b32 s19, v252, 16
	v_lshlrev_b32_e32 v198, 4, v176
	v_lshlrev_b32_e32 v148, 5, v176
	v_add_u32_e32 v149, 0x1000, v148
	v_mov_b32_e32 v116, 0x358637bd
	v_mov_b32_e32 v197, 0
	s_lshl_b32 s1, s58, 4
	s_add_i32 s10, s1, 0xffffff00
	s_mov_b32 s0, s8
	s_ashr_i32 s1, s0, 31
	s_lshl_b64 s[22:23], s[0:1], 12
	global_load_dwordx4 v[84:87], v148, s[14:15]
	global_load_dwordx4 v[88:91], v148, s[14:15] offset:16
	global_load_dwordx4 v[92:95], v148, s[14:15] offset:2048
	global_load_dwordx4 v[96:99], v148, s[14:15] offset:2064
	global_load_dwordx4 v[180:183], v148, s[18:19]
	global_load_dwordx4 v[184:187], v148, s[18:19] offset:16
	global_load_dwordx4 v[188:191], v148, s[18:19] offset:2048
	global_load_dwordx4 v[192:195], v148, s[18:19] offset:2064
	s_add_u32 s20, s20, s22
	s_addc_u32 s21, s21, s23
	s_lshl_b64 s[22:23], s[0:1], 11
	s_add_u32 s24, s54, s22
	s_addc_u32 s25, s55, s23
	s_add_u32 s26, s24, 0x9a00000
	s_addc_u32 s27, s25, 0
	s_add_u32 s24, s24, 0xde00000
	s_addc_u32 s25, s25, 0
	s_lshl_b64 s[22:23], s[0:1], 2
	s_add_u32 s16, s54, s22
	s_addc_u32 s17, s55, s23
	s_add_u32 s16, s16, 0x2280000
	s_addc_u32 s17, s17, 0
	s_lshl_b32 s98, s10, 12
	s_lshl_b32 s99, s10, 11
	s_lshl_b32 s100, s10, 2
	s_mov_b32 s101, 0x800000
.Lx8_loop:
	global_load_dwordx2 v[80:81], v197, s[16:17]
	global_load_dwordx4 v[48:51], v198, s[24:25] nt
	global_load_dwordx4 v[52:55], v198, s[24:25] offset:1024 nt
	global_load_dwordx4 v[16:19], v148, s[20:21] nt
	global_load_dwordx4 v[20:23], v148, s[20:21] offset:16 nt
	global_load_dwordx4 v[24:27], v148, s[20:21] offset:2048 nt
	global_load_dwordx4 v[28:31], v148, s[20:21] offset:2064 nt
	global_load_dwordx4 v[56:59], v198, s[24:25] offset:2048 nt
	global_load_dwordx4 v[60:63], v198, s[24:25] offset:3072 nt
	global_load_dwordx4 v[32:35], v149, s[20:21] nt
	global_load_dwordx4 v[36:39], v149, s[20:21] offset:16 nt
	global_load_dwordx4 v[40:43], v149, s[20:21] offset:2048 nt
	global_load_dwordx4 v[44:47], v149, s[20:21] offset:2064 nt
	s_waitcnt vmcnt(6)
	v_fmamk_f32 v104, v80, 0x3a800000, v116
	v_mul_f32_e32 v105, 0x4b800000, v104
	v_cmp_gt_f32_e32 vcc, s101, v104
	s_nop 1
	v_cndmask_b32_e32 v104, v104, v105, vcc
	v_rsq_f32_e32 v104, v104
	s_nop 0
	v_mul_f32_e32 v105, 0x45800000, v104
	v_cndmask_b32_e32 v104, v104, v105, vcc
	v_lshlrev_b32_e32 v120, 16, v48
	v_and_b32_e32 v121, 0xffff0000, v48
	v_lshlrev_b32_e32 v122, 16, v49
	v_and_b32_e32 v123, 0xffff0000, v49
	v_pk_mul_f32 v[120:121], v[104:105], v[120:121] op_sel_hi:[0,1]
	v_pk_mul_f32 v[122:123], v[104:105], v[122:123] op_sel_hi:[0,1]
	v_pk_fma_f32 v[16:17], v[84:85], v[120:121], v[16:17]
	v_pk_fma_f32 v[18:19], v[86:87], v[122:123], v[18:19]
	v_lshlrev_b32_e32 v124, 16, v50
	v_and_b32_e32 v125, 0xffff0000, v50
	v_lshlrev_b32_e32 v126, 16, v51
	v_and_b32_e32 v127, 0xffff0000, v51
	v_pk_mul_f32 v[124:125], v[104:105], v[124:125] op_sel_hi:[0,1]
	v_pk_mul_f32 v[126:127], v[104:105], v[126:127] op_sel_hi:[0,1]
	v_pk_fma_f32 v[20:21], v[88:89], v[124:125], v[20:21]
	v_pk_fma_f32 v[22:23], v[90:91], v[126:127], v[22:23]
	v_lshlrev_b32_e32 v128, 16, v52
	v_and_b32_e32 v129, 0xffff0000, v52
	v_lshlrev_b32_e32 v130, 16, v53
	v_and_b32_e32 v131, 0xffff0000, v53
	v_pk_mul_f32 v[128:129], v[104:105], v[128:129] op_sel_hi:[0,1]
	v_pk_mul_f32 v[130:131], v[104:105], v[130:131] op_sel_hi:[0,1]
	v_pk_fma_f32 v[24:25], v[92:93], v[128:129], v[24:25]
	v_pk_fma_f32 v[26:27], v[94:95], v[130:131], v[26:27]
	v_lshlrev_b32_e32 v132, 16, v54
	v_and_b32_e32 v133, 0xffff0000, v54
	v_lshlrev_b32_e32 v134, 16, v55
	v_and_b32_e32 v135, 0xffff0000, v55
	v_pk_mul_f32 v[132:133], v[104:105], v[132:133] op_sel_hi:[0,1]
	v_pk_mul_f32 v[134:135], v[104:105], v[134:135] op_sel_hi:[0,1]
	v_pk_fma_f32 v[28:29], v[96:97], v[132:133], v[28:29]
	v_pk_fma_f32 v[30:31], v[98:99], v[134:135], v[30:31]
	v_pk_mul_f32 v[200:201], v[16:17], v[16:17]
	v_pk_fma_f32 v[200:201], v[18:19], v[18:19], v[200:201]
	v_pk_mul_f32 v[202:203], v[20:21], v[20:21]
	v_pk_fma_f32 v[202:203], v[22:23], v[22:23], v[202:203]
	v_pk_add_f32 v[200:201], v[200:201], v[202:203]
	v_pk_mul_f32 v[202:203], v[24:25], v[24:25]
	v_pk_fma_f32 v[202:203], v[26:27], v[26:27], v[202:203]
	v_pk_add_f32 v[200:201], v[200:201], v[202:203]
	v_pk_mul_f32 v[202:203], v[28:29], v[28:29]
	v_pk_fma_f32 v[202:203], v[30:31], v[30:31], v[202:203]
	v_pk_add_f32 v[200:201], v[200:201], v[202:203]
	v_add_f32_e32 v200, v200, v201
	s_nop 1
	v_add_f32_dpp v200, v200, v200 quad_perm:[1,0,3,2] row_mask:0xf bank_mask:0xf
	s_nop 1
	v_add_f32_dpp v200, v200, v200 quad_perm:[2,3,0,1] row_mask:0xf bank_mask:0xf
	s_nop 1
	v_add_f32_dpp v200, v200, v200 row_half_mirror row_mask:0xf bank_mask:0xf
	s_nop 1
	v_add_f32_dpp v200, v200, v200 row_mirror row_mask:0xf bank_mask:0xf
	v_mov_b32_e32 v201, v200
	s_nop 1
	v_permlane16_swap_b32_e32 v200, v201
	v_add_f32_e32 v200, v200, v201
	v_mov_b32_e32 v201, v200
	s_nop 1
	v_permlane32_swap_b32_e32 v200, v201
	v_add_f32_e32 v200, v200, v201
	v_fmamk_f32 v106, v200, 0x3a800000, v116
	v_mul_f32_e32 v107, 0x4b800000, v106
	v_cmp_gt_f32_e32 vcc, s101, v106
	s_nop 1
	v_cndmask_b32_e32 v106, v106, v107, vcc
	v_rsq_f32_e32 v106, v106
	s_nop 0
	v_mul_f32_e32 v107, 0x45800000, v106
	v_cndmask_b32_e32 v106, v106, v107, vcc
	v_pk_mul_f32 v[204:205], v[16:17], v[106:107] op_sel_hi:[1,0]
	v_pk_mul_f32 v[206:207], v[18:19], v[106:107] op_sel_hi:[1,0]
	v_pk_mul_f32 v[204:205], v[180:181], v[204:205]
	v_pk_mul_f32 v[206:207], v[182:183], v[206:207]
	v_pk_mul_f32 v[208:209], v[20:21], v[106:107] op_sel_hi:[1,0]
	v_pk_mul_f32 v[210:211], v[22:23], v[106:107] op_sel_hi:[1,0]
	v_pk_mul_f32 v[208:209], v[184:185], v[208:209]
	v_pk_mul_f32 v[210:211], v[186:187], v[210:211]
	v_pk_mul_f32 v[212:213], v[24:25], v[106:107] op_sel_hi:[1,0]
	v_pk_mul_f32 v[214:215], v[26:27], v[106:107] op_sel_hi:[1,0]
	v_pk_mul_f32 v[212:213], v[188:189], v[212:213]
	v_pk_mul_f32 v[214:215], v[190:191], v[214:215]
	v_pk_mul_f32 v[216:217], v[28:29], v[106:107] op_sel_hi:[1,0]
	v_pk_mul_f32 v[218:219], v[30:31], v[106:107] op_sel_hi:[1,0]
	v_pk_mul_f32 v[216:217], v[192:193], v[216:217]
	v_pk_mul_f32 v[218:219], v[194:195], v[218:219]
	v_cvt_pk_bf16_f32 v220, v204, v205
	v_cvt_pk_bf16_f32 v221, v206, v207
	v_cvt_pk_bf16_f32 v222, v208, v209
	v_cvt_pk_bf16_f32 v223, v210, v211
	v_cvt_pk_bf16_f32 v224, v212, v213
	v_cvt_pk_bf16_f32 v225, v214, v215
	v_cvt_pk_bf16_f32 v226, v216, v217
	v_cvt_pk_bf16_f32 v227, v218, v219
	global_store_dwordx4 v198, v[220:223], s[26:27]
	global_store_dwordx4 v198, v[224:227], s[26:27] offset:1024
	s_waitcnt vmcnt(2)
; __device__ __forceinline__ float wave_sum(float v) { for (int o = 32; o >= 1; o >>= 1) v += __shfl_xor(v, o); return v; }
; __device__ __forceinline__ u32x2 pk4(f32x4 v) { u32x2 w; w.x = cvt_pk_bf16(v[0], v[1]); w.y = cvt_pk_bf16(v[2], v[3]); return w; }
; __device__ __forceinline__ f32x4 up4(u32x2 w) { return (f32x4){bf_lo(w.x), bf_hi(w.x), bf_lo(w.y), bf_hi(w.y)}; }
; __device__ __forceinline__ void row_pass1(const Args& a, int row_lo, int row_hi, int gw, int NGW, int lane) {
;     ...
;         for (int r = 0; r < 2; ++r) { const int row = r0 + r; if (row >= row_hi) break;
;             const float rstd = rsqrtf(rs[r] * (1.f / DM) + EPS); f32x4 v[4]; float s = 0.f;
; #pragma unroll
;             for (int j = 0; j < 4; ++j) { v[j] = xv[r][j] + up4(yv[r][j]) * rstd * gp[j]; s += (v[j][0] * v[j][0] + v[j][1] * v[j][1]) + (v[j][2] * v[j][2] + v[j][3] * v[j][3]); }
;             const float rstd2 = rsqrtf(wave_sum(s) * (1.f / DM) + EPS);
;             f32x4* xo = (f32x4*)(XO + (size_t)row * DM) + lane; u32x2* ao = (u32x2*)(A2 + (size_t)row * DM) + lane;
; #pragma unroll
;             for (int j = 0; j < 4; ++j) { xo[64 * j] = v[j]; ao[64 * j] = pk4(v[j] * rstd2 * gq[j]); } }
	v_fmamk_f32 v104, v81, 0x3a800000, v116
	v_mul_f32_e32 v105, 0x4b800000, v104
	v_cmp_gt_f32_e32 vcc, s101, v104
	s_nop 1
	v_cndmask_b32_e32 v104, v104, v105, vcc
	v_rsq_f32_e32 v104, v104
	s_nop 0
	v_mul_f32_e32 v105, 0x45800000, v104
	v_cndmask_b32_e32 v104, v104, v105, vcc
	v_lshlrev_b32_e32 v120, 16, v56
	v_and_b32_e32 v121, 0xffff0000, v56
	v_lshlrev_b32_e32 v122, 16, v57
	v_and_b32_e32 v123, 0xffff0000, v57
	v_pk_mul_f32 v[120:121], v[104:105], v[120:121] op_sel_hi:[0,1]
	v_pk_mul_f32 v[122:123], v[104:105], v[122:123] op_sel_hi:[0,1]
	v_pk_fma_f32 v[32:33], v[84:85], v[120:121], v[32:33]
	v_pk_fma_f32 v[34:35], v[86:87], v[122:123], v[34:35]
	v_lshlrev_b32_e32 v124, 16, v58
	v_and_b32_e32 v125, 0xffff0000, v58
	v_lshlrev_b32_e32 v126, 16, v59
	v_and_b32_e32 v127, 0xffff0000, v59
	v_pk_mul_f32 v[124:125], v[104:105], v[124:125] op_sel_hi:[0,1]
	v_pk_mul_f32 v[126:127], v[104:105], v[126:127] op_sel_hi:[0,1]
	v_pk_fma_f32 v[36:37], v[88:89], v[124:125], v[36:37]
	v_pk_fma_f32 v[38:39], v[90:91], v[126:127], v[38:39]
	v_lshlrev_b32_e32 v128, 16, v60
	v_and_b32_e32 v129, 0xffff0000, v60
	v_lshlrev_b32_e32 v130, 16, v61
	v_and_b32_e32 v131, 0xffff0000, v61
	v_pk_mul_f32 v[128:129], v[104:105], v[128:129] op_sel_hi:[0,1]
	v_pk_mul_f32 v[130:131], v[104:105], v[130:131] op_sel_hi:[0,1]
	v_pk_fma_f32 v[40:41], v[92:93], v[128:129], v[40:41]
	v_pk_fma_f32 v[42:43], v[94:95], v[130:131], v[42:43]
	v_lshlrev_b32_e32 v132, 16, v62
	v_and_b32_e32 v133, 0xffff0000, v62
	v_lshlrev_b32_e32 v134, 16, v63
	v_and_b32_e32 v135, 0xffff0000, v63
	v_pk_mul_f32 v[132:133], v[104:105], v[132:133] op_sel_hi:[0,1]
	v_pk_mul_f32 v[134:135], v[104:105], v[134:135] op_sel_hi:[0,1]
	v_pk_fma_f32 v[44:45], v[96:97], v[132:133], v[44:45]
	v_pk_fma_f32 v[46:47], v[98:99], v[134:135], v[46:47]
	v_pk_mul_f32 v[200:201], v[32:33], v[32:33]
	v_pk_fma_f32 v[200:201], v[34:35], v[34:35], v[200:201]
	v_pk_mul_f32 v[202:203], v[36:37], v[36:37]
	v_pk_fma_f32 v[202:203], v[38:39], v[38:39], v[202:203]
	v_pk_add_f32 v[200:201], v[200:201], v[202:203]
	v_pk_mul_f32 v[202:203], v[40:41], v[40:41]
	v_pk_fma_f32 v[202:203], v[42:43], v[42:43], v[202:203]
	v_pk_add_f32 v[200:201], v[200:201], v[202:203]
	v_pk_mul_f32 v[202:203], v[44:45], v[44:45]
	v_pk_fma_f32 v[202:203], v[46:47], v[46:47], v[202:203]
	v_pk_add_f32 v[200:201], v[200:201], v[202:203]
	v_add_f32_e32 v200, v200, v201
	s_nop 1
	v_add_f32_dpp v200, v200, v200 quad_perm:[1,0,3,2] row_mask:0xf bank_mask:0xf
	s_nop 1
	v_add_f32_dpp v200, v200, v200 quad_perm:[2,3,0,1] row_mask:0xf bank_mask:0xf
	s_nop 1
	v_add_f32_dpp v200, v200, v200 row_half_mirror row_mask:0xf bank_mask:0xf
	s_nop 1
	v_add_f32_dpp v200, v200, v200 row_mirror row_mask:0xf bank_mask:0xf
	v_mov_b32_e32 v201, v200
	s_nop 1
	v_permlane16_swap_b32_e32 v200, v201
	v_add_f32_e32 v200, v200, v201
	v_mov_b32_e32 v201, v200
	s_nop 1
	v_permlane32_swap_b32_e32 v200, v201
	v_add_f32_e32 v200, v200, v201
	v_fmamk_f32 v106, v200, 0x3a800000, v116
	v_mul_f32_e32 v107, 0x4b800000, v106
	v_cmp_gt_f32_e32 vcc, s101, v106
	s_nop 1
	v_cndmask_b32_e32 v106, v106, v107, vcc
	v_rsq_f32_e32 v106, v106
	s_nop 0
	v_mul_f32_e32 v107, 0x45800000, v106
	v_cndmask_b32_e32 v106, v106, v107, vcc
	v_pk_mul_f32 v[204:205], v[32:33], v[106:107] op_sel_hi:[1,0]
	v_pk_mul_f32 v[206:207], v[34:35], v[106:107] op_sel_hi:[1,0]
	v_pk_mul_f32 v[204:205], v[180:181], v[204:205]
	v_pk_mul_f32 v[206:207], v[182:183], v[206:207]
	v_pk_mul_f32 v[208:209], v[36:37], v[106:107] op_sel_hi:[1,0]
	v_pk_mul_f32 v[210:211], v[38:39], v[106:107] op_sel_hi:[1,0]
	v_pk_mul_f32 v[208:209], v[184:185], v[208:209]
	v_pk_mul_f32 v[210:211], v[186:187], v[210:211]
	v_pk_mul_f32 v[212:213], v[40:41], v[106:107] op_sel_hi:[1,0]
	v_pk_mul_f32 v[214:215], v[42:43], v[106:107] op_sel_hi:[1,0]
	v_pk_mul_f32 v[212:213], v[188:189], v[212:213]
	v_pk_mul_f32 v[214:215], v[190:191], v[214:215]
	v_pk_mul_f32 v[216:217], v[44:45], v[106:107] op_sel_hi:[1,0]
	v_pk_mul_f32 v[218:219], v[46:47], v[106:107] op_sel_hi:[1,0]
	v_pk_mul_f32 v[216:217], v[192:193], v[216:217]
	v_pk_mul_f32 v[218:219], v[194:195], v[218:219]
	v_cvt_pk_bf16_f32 v220, v204, v205
	v_cvt_pk_bf16_f32 v221, v206, v207
	v_cvt_pk_bf16_f32 v222, v208, v209
	v_cvt_pk_bf16_f32 v223, v210, v211
	v_cvt_pk_bf16_f32 v224, v212, v213
	v_cvt_pk_bf16_f32 v225, v214, v215
	v_cvt_pk_bf16_f32 v226, v216, v217
	v_cvt_pk_bf16_f32 v227, v218, v219
	global_store_dwordx4 v198, v[220:223], s[26:27] offset:2048
	global_store_dwordx4 v198, v[224:227], s[26:27] offset:3072
	s_add_i32 s0, s0, s10
	s_add_u32 s20, s20, s98
	s_addc_u32 s21, s21, 0
	s_add_u32 s24, s24, s99
	s_addc_u32 s25, s25, 0
	s_add_u32 s26, s26, s99
	s_addc_u32 s27, s27, 0
	s_add_u32 s16, s16, s100
	s_addc_u32 s17, s17, 0
	s_cmpk_gt_i32 s0, 0x3fff
	s_cbranch_scc0 .Lx8_loop
